# halo split + halo units remapped so the workgroups of one XCD share weights and halo rows in L2
# speedup vs baseline: 1.0186x; 1.0040x over previous
; __global__ void __launch_bounds__(NWAVES * 64, 2) fwd_mega(Args args) {
;     ...
;         if ((int)blockIdx.x >= 88) {
;             ln_rows_range<1, 2, 2>(ZB, XB, nullptr, STATS, IN(21), IN(22), ((int)blockIdx.x - 88) * NWAVES + wave, (M / 64) * 31, (G - 88) * NWAVES, lane);
;         } else {
;             const int pm_ = (int)blockIdx.x / 11;
;             ln_rows_range<1, 1>(ZB, XB, nullptr, STATS, IN(21), IN(22), 64 * pm_ + wave, 64 * pm_ + 64, NWAVES, lane);
.LBB0_670:
	s_or_b64 exec, exec, s[6:7]
	v_readlane_b32 s0, v253, 2
	v_readlane_b32 s1, v253, 3
	s_add_u32 s58, s0, 0x12800000
	s_addc_u32 s59, s1, 0
	s_waitcnt lgkmcnt(0)
	v_mov_b32_e32 v1, v0
	s_add_u32 s16, s0, 0x1f000000
	s_barrier
	s_addc_u32 s17, s1, 0
	v_readfirstlane_b32 s4, v1
	s_ashr_i32 s38, s4, 6
	v_readlane_b32 s0, v253, 0
	s_cmpk_lt_i32 s0, 0x58
	s_cselect_b64 s[60:61], -1, 0
	v_and_b32_e32 v145, 63, v1
	s_mov_b64 s[6:7], -1
	s_and_b64 vcc, exec, s[60:61]
	s_mul_hi_i32 s54, s0, 0x2e8ba2e9
	v_readlane_b32 s1, v253, 1
	s_cbranch_vccz .LBB0_687
	s_lshr_b32 s0, s54, 31
	s_ashr_i32 s3, s54, 1
	s_add_i32 s3, s3, s0
	v_readlane_b32 s98, v253, 0
	s_and_b32 s99, s98, 7
	s_lshr_b32 s98, s98, 3
	s_cmp_lt_u32 s98, 8
	s_cselect_b32 s3, s98, s99
	s_cmp_gt_i32 s38, 63
	s_cbranch_scc1 .LBB0_680
	s_lshl_b32 s2, s3, 6
	v_readlane_b32 s0, v253, 4
	s_add_i32 s19, s38, s2
	v_readlane_b32 s98, v253, 0
	s_and_b32 s99, s98, 7
	s_lshr_b32 s98, s98, 3
	s_cmp_lt_u32 s98, 8
	s_cselect_b32 s98, s99, s98
	s_mul_i32 s99, s38, 11
	s_add_i32 s98, s98, s99
	s_add_i32 s19, s2, s98
	s_cmp_gt_i32 s98, 63
	s_cbranch_scc1 .LBB0_680
	v_readlane_b32 s1, v253, 5
	s_lshl_b32 s5, s19, 6
	s_load_dwordx4 s[8:11], s[0:1], 0xa8
	s_or_b32 s0, s5, 62
	v_readlane_b32 s6, v253, 21
	s_waitcnt vmcnt(5)
	v_lshlrev_b32_e32 v54, 4, v145
	v_mov_b32_e32 v55, 0
	v_readlane_b32 s7, v253, 22
	s_ashr_i32 s1, s0, 31
	s_lshl_b64 s[0:1], s[0:1], 11
	v_lshl_add_u64 v[50:51], s[6:7], 0, v[54:55]
	v_lshl_add_u64 v[2:3], v[50:51], 0, s[0:1]
	s_or_b32 s0, s5, 63
	s_ashr_i32 s1, s0, 31
	s_lshl_b64 s[0:1], s[0:1], 11
	global_load_dwordx4 v[38:41], v[2:3], off
	global_load_dwordx4 v[42:45], v[2:3], off offset:1024
	v_lshl_add_u64 v[2:3], v[50:51], 0, s[0:1]
	v_lshlrev_b32_e32 v52, 5, v145
	global_load_dwordx4 v[34:37], v[2:3], off
	global_load_dwordx4 v[46:49], v[2:3], off offset:1024
	s_waitcnt lgkmcnt(0)
	global_load_dwordx4 v[2:5], v52, s[8:9] offset:16
	global_load_dwordx4 v[6:9], v52, s[10:11] offset:16
	global_load_dwordx4 v[10:13], v52, s[8:9]
	global_load_dwordx4 v[14:17], v52, s[10:11]
	global_load_dwordx4 v[18:21], v52, s[8:9] offset:2064
	global_load_dwordx4 v[22:25], v52, s[10:11] offset:2064
	global_load_dwordx4 v[26:29], v52, s[8:9] offset:2048
	global_load_dwordx4 v[30:33], v52, s[10:11] offset:2048
	v_readlane_b32 s0, v253, 23
	v_readlane_b32 s1, v253, 24
	s_mov_b32 s5, 0
	v_mov_b32_e32 v93, 0x3727c5ac
	v_lshl_add_u64 v[52:53], s[0:1], 0, v[54:55]
	v_or_b32_e32 v54, 0x400, v54
	v_lshl_add_u64 v[54:55], s[0:1], 0, v[54:55]
	s_lshl_b32 s0, s19, 6
	s_or_b32 s10, s0, 63
	s_mov_b32 s18, 0xf800000
	v_mov_b32_e32 v95, 0x260
	s_branch .LBB0_674

; #define LAS __attribute__((address_space(3)))
; __device__ __forceinline__ void halo_gemm_unit(int unit, int tid, int lane, int wave, LAS unsigned char* lds, const bf16_t* __restrict__ XBp, const bf16_t* __restrict__ Wup, bf16_t* __restrict__ HALOp) {
;     const int pm = unit / 11, pn = unit - pm * 11, wr = wave >> 2, wc = wave & 3, l31 = lane & 31, hi = lane >> 5;
;     const int srow = tid >> 3, sch = tid & 7;
;     const bf16_t* gA[2]; const bf16_t* gB[4]; int lA[2], lB[4];
; #pragma unroll
;     for (int i = 0; i < 2; ++i) { const int row = srow + 64 * i, R = 128 * pm + row; gA[i] = XBp + (size_t)(64 * (R >> 1) + 62 + (R & 1)) * DM + sch * 8; lA[i] = row * HG_PITCH + sch * 16; }
; #pragma unroll
;     for (int i = 0; i < 4; ++i) { const int row = srow + 64 * i, ch = 256 * pn + row; gB[i] = Wup + (size_t)(256 * (ch >> 7) + (ch & 127)) * 1024 + sch * 8; lB[i] = HG_A_BYTES + row * HG_PITCH + sch * 16; }
;     f32x16 acc[2][2];
; #pragma unroll
;     for (int a = 0; a < 2; ++a)
; #pragma unroll
;         for (int b = 0; b < 2; ++b)
; #pragma unroll
;             for (int r = 0; r < 16; ++r) acc[a][b][r] = 0.f;
;     v4u ra0[2], rb0[4], ra1[2], rb1[4];
; #pragma unroll
;     for (int i = 0; i < 2; ++i) ra0[i] = *(const v4u*)gA[i];
; #pragma unroll
;     for (int i = 0; i < 4; ++i) rb0[i] = *(const v4u*)gB[i];
; #pragma unroll
;     for (int i = 0; i < 2; ++i) ra1[i] = *(const v4u*)(gA[i] + 64);
; #pragma unroll
;     for (int i = 0; i < 4; ++i) rb1[i] = *(const v4u*)(gB[i] + 64);
; #pragma unroll
;     for (int i = 0; i < 2; ++i) *(LAS v4u*)(lds + lA[i]) = ra0[i];
; #pragma unroll
;     for (int i = 0; i < 4; ++i) *(LAS v4u*)(lds + lB[i]) = rb0[i];
;     __syncthreads();
.LBB0_682:
	s_or_b64 exec, exec, s[6:7]
	s_waitcnt vmcnt(13)
	v_ashrrev_i32_e32 v28, 3, v1
	s_lshl_b32 s0, s3, 12
	v_and_or_b32 v8, v28, 1, s0
	v_lshl_add_u32 v6, v28, 5, v8
	v_lshlrev_b32_e32 v2, 4, v1
	v_readlane_b32 s0, v253, 23
	v_or_b32_e32 v6, 62, v6
	v_and_b32_e32 v2, 0x70, v2
	v_mov_b32_e32 v3, 0
	v_readlane_b32 s1, v253, 24
	v_ashrrev_i32_e32 v7, 31, v6
	v_lshlrev_b64 v[6:7], 11, v[6:7]
	v_lshl_add_u64 v[4:5], s[0:1], 0, v[2:3]
	v_add_u32_e32 v9, 64, v28
	s_mul_i32 s5, s3, -11
	s_waitcnt vmcnt(8)
	v_lshl_add_u64 v[114:115], v[4:5], 0, v[6:7]
	v_lshl_add_u32 v6, v9, 5, v8
	v_readlane_b32 s0, v253, 0
	v_or_b32_e32 v6, 62, v6
	s_add_i32 s5, s5, s0
	v_readlane_b32 s98, v253, 0
	s_and_b32 s99, s98, 7
	s_lshr_b32 s98, s98, 3
	s_cmp_lt_u32 s98, 8
	s_cselect_b32 s5, s99, s98
	v_ashrrev_i32_e32 v7, 31, v6
	v_readlane_b32 s1, v253, 1
	s_lshl_b32 s0, s5, 9
	v_lshlrev_b64 v[6:7], 11, v[6:7]
	v_lshl_add_u32 v8, v28, 1, s0
	v_and_b32_e32 v10, 0x7f, v28
	s_movk_i32 s1, 0xff00
	v_lshl_add_u64 v[116:117], v[4:5], 0, v[6:7]
	v_readlane_b32 s6, v253, 31
	v_and_or_b32 v6, v8, s1, v10
	v_readlane_b32 s7, v253, 32
	v_ashrrev_i32_e32 v7, 31, v6
	v_lshlrev_b64 v[6:7], 11, v[6:7]
	v_lshl_add_u64 v[4:5], s[6:7], 0, v[2:3]
	s_waitcnt vmcnt(2)
	v_lshl_add_u64 v[118:119], v[4:5], 0, v[6:7]
	v_lshl_add_u32 v6, v9, 1, s0
	v_and_b32_e32 v7, 0x7f, v9
	v_and_or_b32 v6, v6, s1, v7
	v_ashrrev_i32_e32 v7, 31, v6
	v_lshlrev_b64 v[6:7], 11, v[6:7]
	v_lshl_add_u64 v[120:121], v[4:5], 0, v[6:7]
	v_add_u32_e32 v6, 0x100, v8
	v_and_or_b32 v6, v6, s1, v10
	v_ashrrev_i32_e32 v7, 31, v6
	v_lshlrev_b64 v[6:7], 11, v[6:7]
	v_lshl_add_u64 v[122:123], v[4:5], 0, v[6:7]
	v_add_u32_e32 v6, 0xc0, v28
	v_lshl_add_u32 v7, v6, 1, s0
	v_and_b32_e32 v6, 0x7f, v6
	v_and_or_b32 v6, v7, s1, v6
	v_ashrrev_i32_e32 v7, 31, v6
	v_lshlrev_b64 v[6:7], 11, v[6:7]
	s_barrier
	v_lshl_add_u64 v[124:125], v[4:5], 0, v[6:7]
	global_load_dwordx4 v[4:7], v[114:115], off
	global_load_dwordx4 v[8:11], v[116:117], off
	global_load_dwordx4 v[12:15], v[118:119], off
	global_load_dwordx4 v[16:19], v[120:121], off
	global_load_dwordx4 v[20:23], v[122:123], off
	global_load_dwordx4 v[24:27], v[124:125], off
	global_load_dwordx4 v[66:69], v[114:115], off offset:128
	global_load_dwordx4 v[70:73], v[116:117], off offset:128
	global_load_dwordx4 v[74:77], v[118:119], off offset:128
	global_load_dwordx4 v[78:81], v[120:121], off offset:128
	global_load_dwordx4 v[82:85], v[124:125], off offset:128
	global_load_dwordx4 v[86:89], v[122:123], off offset:128
	s_movk_i32 s2, 0x90
	v_mul_lo_u32 v28, v28, s2
	v_add_u32_e32 v29, v28, v2
	v_add_u32_e32 v30, 0x2400, v28
	v_add_u32_e32 v32, 0x4800, v28
	v_add_u32_e32 v33, 0x6c00, v28
	s_lshl_b32 s11, s38, 4
	v_and_b32_e32 v126, 31, v1
	v_lshrrev_b32_e32 v127, 5, v145
	v_or_b32_e32 v31, 0x4800, v2
	v_add_u32_e32 v34, v30, v2
	v_add_u32_e32 v128, 0, v29
	v_add_u32_e32 v29, v2, v32
	v_add_u32_e32 v2, v2, v33
	s_andn2_b32 s11, s11, 63
	v_add_u32_e32 v129, 0, v34
	v_add_u32_e32 v130, 0, v29
	v_add_u32_e32 v131, 0, v2
	v_lshlrev_b32_e32 v2, 4, v127
	s_and_b32 s4, s4, 0xc0
	v_add_u32_e32 v28, v31, v28
	v_add_u32_e32 v30, v31, v30
	v_add_u32_e32 v35, v31, v32
	v_add_u32_e32 v31, v31, v33
	s_movk_i32 s10, 0xc0
	s_mov_b32 s7, 0
	v_add_u32_e32 v134, 0, v28
	v_add_u32_e32 v135, 0, v30
	v_add_u32_e32 v136, 0, v35
	v_add_u32_e32 v137, 0, v31
	s_mov_b32 s12, 0
	v_mov_b32_e32 v28, v3
	v_mov_b32_e32 v29, v3
	v_mov_b32_e32 v30, v3
	v_mov_b32_e32 v31, v3
	v_mov_b32_e32 v32, v3
	v_mov_b32_e32 v33, v3
	v_mov_b32_e32 v34, v3
	v_mov_b32_e32 v35, v3
	v_mov_b32_e32 v36, v3
	v_mov_b32_e32 v37, v3
	v_mov_b32_e32 v38, v3
	v_mov_b32_e32 v39, v3
	v_mov_b32_e32 v40, v3
	v_mov_b32_e32 v41, v3
	v_mov_b32_e32 v42, v3
	v_mov_b32_e32 v43, v3
	v_mov_b32_e32 v44, v3
	s_waitcnt vmcnt(11)
	ds_write_b128 v128, v[4:7]
	s_waitcnt vmcnt(10)
	ds_write_b128 v129, v[8:11]
	s_waitcnt vmcnt(9)
	ds_write_b128 v128, v[12:15] offset:18432
	s_waitcnt vmcnt(8)
	ds_write_b128 v129, v[16:19] offset:18432
	s_waitcnt vmcnt(7)
	ds_write_b128 v130, v[20:23] offset:18432
	s_waitcnt vmcnt(6)
	ds_write_b128 v131, v[24:27] offset:18432
	v_or_b32_e32 v4, s11, v126
	v_mad_u64_u32 v[4:5], s[0:1], v4, s2, v[2:3]
	v_or_b32_e32 v5, s4, v126
	v_mad_u32_u24 v132, v5, s2, v2
	v_add_u32_e32 v2, 0x4800, v132
	v_add_u32_e32 v133, 0, v4
	v_add_u32_e32 v138, 0, v2
	v_mov_b32_e32 v2, v3
	v_mov_b32_e32 v4, v3
	v_mov_b32_e32 v5, v3
	v_mov_b32_e32 v6, v3
	v_mov_b32_e32 v7, v3
	v_mov_b32_e32 v8, v3
	v_mov_b32_e32 v9, v3
	v_mov_b32_e32 v10, v3
	v_mov_b32_e32 v11, v3
	v_mov_b32_e32 v12, v3
	v_mov_b32_e32 v13, v3
	v_mov_b32_e32 v14, v3
	v_mov_b32_e32 v15, v3
	v_mov_b32_e32 v16, v3
	v_mov_b32_e32 v17, v3
	v_mov_b32_e32 v18, v3
	v_mov_b32_e32 v19, v3
	v_mov_b32_e32 v20, v3
	v_mov_b32_e32 v21, v3
	v_mov_b32_e32 v22, v3
	v_mov_b32_e32 v23, v3
	v_mov_b32_e32 v24, v3
	v_mov_b32_e32 v25, v3
	v_mov_b32_e32 v26, v3
	v_mov_b32_e32 v27, v3
	v_mov_b32_e32 v45, v3
	v_mov_b32_e32 v46, v3
	v_mov_b32_e32 v47, v3
	v_mov_b32_e32 v48, v3
	v_mov_b32_e32 v49, v3
	v_mov_b32_e32 v50, v3
	v_mov_b32_e32 v51, v3
	v_mov_b32_e32 v52, v3
	v_mov_b32_e32 v53, v3
	v_mov_b32_e32 v54, v3
	v_mov_b32_e32 v55, v3
	v_mov_b32_e32 v56, v3
	v_mov_b32_e32 v57, v3
	v_mov_b32_e32 v58, v3
	v_mov_b32_e32 v59, v3
	v_mov_b32_e32 v60, v3
	v_mov_b32_e32 v61, v3
	v_mov_b32_e32 v62, v3
	v_mov_b32_e32 v63, v3
	v_mov_b32_e32 v64, v3
	v_mov_b32_e32 v65, v3
	s_waitcnt lgkmcnt(0)
	s_barrier
	s_branch .LBB0_684

; __global__ void __launch_bounds__(NWAVES * 64, 2) fwd_mega(Args args) {
;     ...
;         } else {
;             const int pm_ = (int)blockIdx.x / 11;
;             ln_rows_range<1, 1>(ZB, XB, nullptr, STATS, IN(35), IN(36), 64 * pm_ + wave, 64 * pm_ + 64, NWAVES, lane);
.LBB0_1742:
	s_or_b64 exec, exec, s[8:9]
	v_mov_b32_e32 v93, v0
	s_waitcnt lgkmcnt(0)
	s_barrier
	s_mov_b64 s[8:9], -1
	v_readfirstlane_b32 s4, v93
	v_and_b32_e32 v1, 63, v93
	s_ashr_i32 s6, s4, 6
	s_and_b64 vcc, exec, s[60:61]
	s_cbranch_vccz .LBB0_1759
	s_lshr_b32 s0, s54, 31
	s_ashr_i32 s7, s54, 1
	s_add_i32 s7, s7, s0
	v_readlane_b32 s98, v253, 0
	s_and_b32 s99, s98, 7
	s_lshr_b32 s98, s98, 3
	s_cmp_lt_u32 s98, 8
	s_cselect_b32 s7, s98, s99
	s_cmp_gt_i32 s6, 63
	s_cbranch_scc1 .LBB0_1752
	s_lshl_b32 s2, s7, 6
	v_readlane_b32 s0, v253, 4
	s_add_i32 s15, s6, s2
	v_readlane_b32 s98, v253, 0
	s_and_b32 s99, s98, 7
	s_lshr_b32 s98, s98, 3
	s_cmp_lt_u32 s98, 8
	s_cselect_b32 s98, s99, s98
	s_mul_i32 s99, s6, 11
	s_add_i32 s98, s98, s99
	s_add_i32 s15, s2, s98
	s_cmp_gt_i32 s98, 63
	s_cbranch_scc1 .LBB0_1752
	v_readlane_b32 s1, v253, 5
	s_lshl_b32 s3, s15, 6
	s_load_dwordx4 s[8:11], s[0:1], 0x118
	s_or_b32 s0, s3, 62
	v_readlane_b32 s12, v253, 21
	v_lshlrev_b32_e32 v54, 4, v1
	v_mov_b32_e32 v55, 0
	v_readlane_b32 s13, v253, 22
	s_ashr_i32 s1, s0, 31
	s_lshl_b64 s[0:1], s[0:1], 11
	v_lshl_add_u64 v[50:51], s[12:13], 0, v[54:55]
	v_lshl_add_u64 v[2:3], v[50:51], 0, s[0:1]
	s_or_b32 s0, s3, 63
	s_ashr_i32 s1, s0, 31
	s_lshl_b64 s[0:1], s[0:1], 11
	global_load_dwordx4 v[38:41], v[2:3], off
	global_load_dwordx4 v[42:45], v[2:3], off offset:1024
	v_lshl_add_u64 v[2:3], v[50:51], 0, s[0:1]
	v_lshlrev_b32_e32 v52, 5, v1
	global_load_dwordx4 v[34:37], v[2:3], off
	global_load_dwordx4 v[46:49], v[2:3], off offset:1024
	s_waitcnt lgkmcnt(0)
	global_load_dwordx4 v[2:5], v52, s[8:9] offset:16
	global_load_dwordx4 v[6:9], v52, s[10:11] offset:16
	global_load_dwordx4 v[10:13], v52, s[8:9]
	global_load_dwordx4 v[14:17], v52, s[10:11]
	global_load_dwordx4 v[18:21], v52, s[8:9] offset:2064
	global_load_dwordx4 v[22:25], v52, s[10:11] offset:2064
	global_load_dwordx4 v[26:29], v52, s[8:9] offset:2048
	global_load_dwordx4 v[30:33], v52, s[10:11] offset:2048
	v_readlane_b32 s0, v253, 23
	v_readlane_b32 s1, v253, 24
	s_mov_b32 s5, 0
	v_mov_b32_e32 v95, 0x3727c5ac
	v_lshl_add_u64 v[52:53], s[0:1], 0, v[54:55]
	v_or_b32_e32 v54, 0x400, v54
	v_lshl_add_u64 v[54:55], s[0:1], 0, v[54:55]
	s_lshl_b32 s0, s15, 6
	s_or_b32 s12, s0, 63
	s_mov_b32 s14, 0xf800000
	v_mov_b32_e32 v96, 0x260
	s_branch .LBB0_1746

; #define LAS __attribute__((address_space(3)))
; __device__ __forceinline__ void halo_gemm_unit(int unit, int tid, int lane, int wave, LAS unsigned char* lds, const bf16_t* __restrict__ XBp, const bf16_t* __restrict__ Wup, bf16_t* __restrict__ HALOp) {
;     const int pm = unit / 11, pn = unit - pm * 11, wr = wave >> 2, wc = wave & 3, l31 = lane & 31, hi = lane >> 5;
;     const int srow = tid >> 3, sch = tid & 7;
;     const bf16_t* gA[2]; const bf16_t* gB[4]; int lA[2], lB[4];
; #pragma unroll
;     for (int i = 0; i < 2; ++i) { const int row = srow + 64 * i, R = 128 * pm + row; gA[i] = XBp + (size_t)(64 * (R >> 1) + 62 + (R & 1)) * DM + sch * 8; lA[i] = row * HG_PITCH + sch * 16; }
; #pragma unroll
;     for (int i = 0; i < 4; ++i) { const int row = srow + 64 * i, ch = 256 * pn + row; gB[i] = Wup + (size_t)(256 * (ch >> 7) + (ch & 127)) * 1024 + sch * 8; lB[i] = HG_A_BYTES + row * HG_PITCH + sch * 16; }
;     f32x16 acc[2][2];
; #pragma unroll
;     for (int a = 0; a < 2; ++a)
; #pragma unroll
;         for (int b = 0; b < 2; ++b)
; #pragma unroll
;             for (int r = 0; r < 16; ++r) acc[a][b][r] = 0.f;
;     v4u ra0[2], rb0[4], ra1[2], rb1[4];
; #pragma unroll
;     for (int i = 0; i < 2; ++i) ra0[i] = *(const v4u*)gA[i];
; #pragma unroll
;     for (int i = 0; i < 4; ++i) rb0[i] = *(const v4u*)gB[i];
; #pragma unroll
;     for (int i = 0; i < 2; ++i) ra1[i] = *(const v4u*)(gA[i] + 64);
; #pragma unroll
;     for (int i = 0; i < 4; ++i) rb1[i] = *(const v4u*)(gB[i] + 64);
; #pragma unroll
;     for (int i = 0; i < 2; ++i) *(LAS v4u*)(lds + lA[i]) = ra0[i];
; #pragma unroll
;     for (int i = 0; i < 4; ++i) *(LAS v4u*)(lds + lB[i]) = rb0[i];
;     __syncthreads();
.LBB0_1754:
	s_or_b64 exec, exec, s[8:9]
	v_ashrrev_i32_e32 v28, 3, v93
	s_lshl_b32 s0, s7, 12
	v_and_or_b32 v8, v28, 1, s0
	v_lshl_add_u32 v6, v28, 5, v8
	v_lshlrev_b32_e32 v2, 4, v93
	v_readlane_b32 s0, v253, 23
	v_or_b32_e32 v6, 62, v6
	v_and_b32_e32 v2, 0x70, v2
	v_mov_b32_e32 v3, 0
	v_readlane_b32 s1, v253, 24
	v_ashrrev_i32_e32 v7, 31, v6
	v_lshlrev_b64 v[6:7], 11, v[6:7]
	v_lshl_add_u64 v[4:5], s[0:1], 0, v[2:3]
	v_add_u32_e32 v9, 64, v28
	s_mul_i32 s5, s7, -11
	v_lshl_add_u64 v[114:115], v[4:5], 0, v[6:7]
	v_lshl_add_u32 v6, v9, 5, v8
	v_or_b32_e32 v6, 62, v6
	s_add_i32 s5, s5, s52
	v_readlane_b32 s98, v253, 0
	s_and_b32 s99, s98, 7
	s_lshr_b32 s98, s98, 3
	s_cmp_lt_u32 s98, 8
	s_cselect_b32 s5, s99, s98
	v_ashrrev_i32_e32 v7, 31, v6
	s_lshl_b32 s0, s5, 9
	v_lshlrev_b64 v[6:7], 11, v[6:7]
	v_lshl_add_u32 v8, v28, 1, s0
	v_and_b32_e32 v10, 0x7f, v28
	s_movk_i32 s1, 0xff00
	v_lshl_add_u64 v[116:117], v[4:5], 0, v[6:7]
	v_and_or_b32 v6, v8, s1, v10
	v_ashrrev_i32_e32 v7, 31, v6
	v_lshl_add_u64 v[4:5], s[24:25], 0, v[2:3]
	v_lshlrev_b64 v[6:7], 11, v[6:7]
	v_lshl_add_u64 v[118:119], v[4:5], 0, v[6:7]
	v_lshl_add_u32 v6, v9, 1, s0
	v_and_b32_e32 v7, 0x7f, v9
	v_and_or_b32 v6, v6, s1, v7
	v_ashrrev_i32_e32 v7, 31, v6
	v_lshlrev_b64 v[6:7], 11, v[6:7]
	v_lshl_add_u64 v[120:121], v[4:5], 0, v[6:7]
	v_add_u32_e32 v6, 0x100, v8
	v_and_or_b32 v6, v6, s1, v10
	v_ashrrev_i32_e32 v7, 31, v6
	v_lshlrev_b64 v[6:7], 11, v[6:7]
	v_lshl_add_u64 v[122:123], v[4:5], 0, v[6:7]
	v_add_u32_e32 v6, 0xc0, v28
	v_lshl_add_u32 v7, v6, 1, s0
	v_and_b32_e32 v6, 0x7f, v6
	v_and_or_b32 v6, v7, s1, v6
	v_ashrrev_i32_e32 v7, 31, v6
	v_lshlrev_b64 v[6:7], 11, v[6:7]
	s_barrier
	v_lshl_add_u64 v[124:125], v[4:5], 0, v[6:7]
	global_load_dwordx4 v[4:7], v[114:115], off
	global_load_dwordx4 v[8:11], v[116:117], off
	global_load_dwordx4 v[12:15], v[118:119], off
	global_load_dwordx4 v[16:19], v[120:121], off
	global_load_dwordx4 v[20:23], v[122:123], off
	global_load_dwordx4 v[24:27], v[124:125], off
	global_load_dwordx4 v[66:69], v[114:115], off offset:128
	global_load_dwordx4 v[70:73], v[116:117], off offset:128
	global_load_dwordx4 v[74:77], v[118:119], off offset:128
	global_load_dwordx4 v[78:81], v[120:121], off offset:128
	global_load_dwordx4 v[82:85], v[124:125], off offset:128
	global_load_dwordx4 v[86:89], v[122:123], off offset:128
	s_movk_i32 s2, 0x90
	v_mul_lo_u32 v28, v28, s2
	v_add_u32_e32 v29, v28, v2
	v_add_u32_e32 v30, 0x2400, v28
	v_add_u32_e32 v32, 0x4800, v28
	v_add_u32_e32 v33, 0x6c00, v28
	s_lshl_b32 s13, s6, 4
	v_and_b32_e32 v126, 31, v93
	v_lshrrev_b32_e32 v127, 5, v1
	v_or_b32_e32 v31, 0x4800, v2
	s_waitcnt vmcnt(17)
	v_add_u32_e32 v34, v30, v2
	v_add_u32_e32 v128, 0, v29
	v_add_u32_e32 v29, v2, v32
	v_add_u32_e32 v2, v2, v33
	s_andn2_b32 s13, s13, 63
	v_add_u32_e32 v129, 0, v34
	v_add_u32_e32 v130, 0, v29
	v_add_u32_e32 v131, 0, v2
	v_lshlrev_b32_e32 v2, 4, v127
	s_and_b32 s4, s4, 0xc0
	v_add_u32_e32 v28, v31, v28
	v_add_u32_e32 v30, v31, v30
	v_add_u32_e32 v35, v31, v32
	v_add_u32_e32 v31, v31, v33
	s_movk_i32 s12, 0xc0
	s_mov_b32 s9, 0
	v_add_u32_e32 v134, 0, v28
	v_add_u32_e32 v135, 0, v30
	v_add_u32_e32 v136, 0, v35
	v_add_u32_e32 v137, 0, v31
	s_mov_b32 s14, 0
	v_mov_b32_e32 v28, v3
	v_mov_b32_e32 v29, v3
	v_mov_b32_e32 v30, v3
	v_mov_b32_e32 v31, v3
	v_mov_b32_e32 v32, v3
	v_mov_b32_e32 v33, v3
	v_mov_b32_e32 v34, v3
	v_mov_b32_e32 v35, v3
	v_mov_b32_e32 v36, v3
	v_mov_b32_e32 v37, v3
	v_mov_b32_e32 v38, v3
	v_mov_b32_e32 v39, v3
	v_mov_b32_e32 v40, v3
	v_mov_b32_e32 v41, v3
	v_mov_b32_e32 v42, v3
	v_mov_b32_e32 v43, v3
	v_mov_b32_e32 v44, v3
	v_mov_b32_e32 v45, v3
	s_waitcnt vmcnt(16)
	v_mov_b32_e32 v46, v3
	v_mov_b32_e32 v47, v3
	v_mov_b32_e32 v48, v3
	s_waitcnt vmcnt(11)
	ds_write_b128 v128, v[4:7]
	s_waitcnt vmcnt(10)
	ds_write_b128 v129, v[8:11]
	s_waitcnt vmcnt(9)
	ds_write_b128 v128, v[12:15] offset:18432
	s_waitcnt vmcnt(8)
	ds_write_b128 v129, v[16:19] offset:18432
	s_waitcnt vmcnt(7)
	ds_write_b128 v130, v[20:23] offset:18432
	s_waitcnt vmcnt(6)
	ds_write_b128 v131, v[24:27] offset:18432
	v_or_b32_e32 v4, s13, v126
	v_mad_u64_u32 v[4:5], s[0:1], v4, s2, v[2:3]
	v_or_b32_e32 v5, s4, v126
	v_mad_u32_u24 v132, v5, s2, v2
	v_add_u32_e32 v2, 0x4800, v132
	v_add_u32_e32 v133, 0, v4
	v_add_u32_e32 v138, 0, v2
	v_mov_b32_e32 v2, v3
	v_mov_b32_e32 v4, v3
	v_mov_b32_e32 v5, v3
	v_mov_b32_e32 v6, v3
	v_mov_b32_e32 v7, v3
	v_mov_b32_e32 v8, v3
	v_mov_b32_e32 v9, v3
	v_mov_b32_e32 v10, v3
	v_mov_b32_e32 v11, v3
	v_mov_b32_e32 v12, v3
	v_mov_b32_e32 v13, v3
	v_mov_b32_e32 v14, v3
	v_mov_b32_e32 v15, v3
	v_mov_b32_e32 v16, v3
	v_mov_b32_e32 v17, v3
	v_mov_b32_e32 v18, v3
	v_mov_b32_e32 v19, v3
	v_mov_b32_e32 v20, v3
	v_mov_b32_e32 v21, v3
	v_mov_b32_e32 v22, v3
	v_mov_b32_e32 v23, v3
	v_mov_b32_e32 v24, v3
	v_mov_b32_e32 v25, v3
	v_mov_b32_e32 v26, v3
	v_mov_b32_e32 v27, v3
	v_mov_b32_e32 v49, v3
	v_mov_b32_e32 v50, v3
	v_mov_b32_e32 v51, v3
	v_mov_b32_e32 v52, v3
	v_mov_b32_e32 v53, v3
	v_mov_b32_e32 v54, v3
	v_mov_b32_e32 v55, v3
	v_mov_b32_e32 v56, v3
	v_mov_b32_e32 v57, v3
	v_mov_b32_e32 v58, v3
	v_mov_b32_e32 v59, v3
	v_mov_b32_e32 v60, v3
	v_mov_b32_e32 v61, v3
	v_mov_b32_e32 v62, v3
	v_mov_b32_e32 v63, v3
	v_mov_b32_e32 v64, v3
	v_mov_b32_e32 v65, v3
	s_waitcnt lgkmcnt(0)
	s_barrier
	s_branch .LBB0_1756
